# grid barrier: the acquire (buffer_inv sc1) is issued when the workgroup arrives instead of after the release is seen - nothing of the workgroup loads through the L1 until the barrier opens - and is wa
# speedup vs baseline: 1.1655x; 1.0065x over previous
.Lxb_go:
	s_mov_b64 exec, 1
	v_readlane_b32 s24, v255, 13
	v_readlane_b32 s25, v255, 14
	s_add_u32 s36, s30, 0x1400
	s_addc_u32 s37, s31, 0
	s_add_u32 s36, s36, s22
	s_addc_u32 s37, s37, 0
	s_add_u32 s38, s30, 0x2400
	s_addc_u32 s39, s31, 0
	s_add_i32 s21, s23, 1
	v_writelane_b32 v255, s21, 12
	s_mul_i32 s24, s24, s21
	s_mul_i32 s25, s25, s21
	v_mov_b32_e32 v2, 1
	buffer_inv sc1
	global_atomic_add v3, v4, v2, s[36:37] sc0
	s_waitcnt vmcnt(0)
	v_readfirstlane_b32 s21, v3
	s_add_i32 s21, s21, 1
	s_cmp_lg_u32 s21, s24
	s_cbranch_scc1 .Lxb_wait
	buffer_wbl2 sc1
	s_add_u32 s36, s30, 0x3400
	s_addc_u32 s37, s31, 0
	s_waitcnt vmcnt(0)
	global_atomic_add v3, v4, v2, s[36:37] sc0
	s_waitcnt vmcnt(0)
	v_readfirstlane_b32 s21, v3
	s_add_i32 s21, s21, 1
	s_cmp_lg_u32 s21, s25
	s_cbranch_scc1 .Lxb_wait
	s_mov_b64 exec, 0xffff
	v_mbcnt_lo_u32_b32 v3, -1, 0
	v_mov_b32_e32 v2, 1
	v_lshlrev_b32_e32 v3, 8, v3
	global_atomic_add v3, v2, s[38:39]
	s_mov_b64 exec, 1
	s_branch .Lxb_acq

.Lxb_acq:
	s_mov_b64 exec, -1
